# w_up stored K-tile-blocked in LDS-image order (conversion store addresses), up-GEMM stages B linearly; w_up tail batches converted in the in-phase
# baseline (speedup 1.0000x reference)
.LBB0_70:
	s_mov_b64 s[38:39], s[30:31]
	s_mov_b64 s[38:39], s[30:31]
	s_mov_b64 s[38:39], s[30:31]
	s_mov_b64 s[38:39], s[30:31]
	s_mov_b64 s[40:41], s[30:31]
	s_mov_b64 s[42:43], s[30:31]
	s_mov_b64 s[44:45], s[30:31]
	s_mov_b64 s[64:65], s[30:31]
	s_mov_b64 s[38:39], s[30:31]
	s_mov_b64 s[38:39], s[30:31]
	s_mov_b64 s[38:39], s[30:31]
	s_mov_b64 s[38:39], s[30:31]
	s_mov_b64 s[38:39], s[30:31]
	s_mov_b64 s[38:39], s[30:31]
	s_mov_b64 s[38:39], s[30:31]
	s_mov_b64 s[38:39], s[30:31]
	s_mov_b64 s[38:39], s[30:31]
	s_mov_b64 s[38:39], s[30:31]
	s_mov_b32 s18, 0x20470
	s_add_i32 s18, s18, 0
	v_mov_b32_e32 v2, s18
	ds_read_b64 v[4:5], v2
	s_mov_b32 s18, 0x204e0
	s_add_i32 s18, s18, 0
	v_mov_b32_e32 v2, s18
	s_waitcnt lgkmcnt(0)
	v_readfirstlane_b32 s69, v5
	v_readfirstlane_b32 s68, v4
	ds_read_b64 v[4:5], v2
	s_mov_b32 s18, 0x204e8
	s_add_i32 s18, s18, 0
	v_mov_b32_e32 v2, s18
	s_waitcnt lgkmcnt(0)
	v_readfirstlane_b32 s47, v5
	v_readfirstlane_b32 s46, v4
	ds_read_b64 v[4:5], v2
	s_mov_b32 s18, 0x204f0
	s_add_i32 s18, s18, 0
	v_mov_b32_e32 v2, s18
	s_waitcnt lgkmcnt(0)
	v_readfirstlane_b32 s55, v5
	v_readfirstlane_b32 s54, v4
	ds_read_b64 v[4:5], v2
	s_andn2_b64 vcc, exec, s[78:79]
	s_waitcnt lgkmcnt(0)
	v_readfirstlane_b32 s57, v5
	v_readfirstlane_b32 s56, v4
	s_cbranch_vccnz .LBB0_69
	s_and_b64 s[38:39], s[2:3], exec
	s_cselect_b32 s18, 0x360, 0
	s_and_b64 s[38:39], s[62:63], exec
	s_cselect_b32 s38, 0x130, s18
	s_and_b64 vcc, s[2:3], s[74:75]
	s_and_b64 vcc, vcc, exec
	s_cselect_b32 s18, 0xd0, 0
	s_and_b64 s[62:63], s[62:63], exec
	s_cselect_b32 s18, 0, s18
	s_and_b64 s[62:63], s[2:3], exec
	s_cselect_b32 s39, 0x360, 0
	s_add_i32 s18, s18, s82
	s_mul_hi_u32 s62, s18, s72
	s_mul_i32 s62, s62, s76
	s_sub_i32 s18, s18, s62
	s_sub_i32 s62, s18, s76
	s_cmp_ge_u32 s18, s76
	s_cselect_b32 s18, s62, s18
	s_sub_i32 s62, s18, s76
	s_cmp_ge_u32 s18, s76
	s_cselect_b32 s18, s62, s18
	s_add_i32 s39, s18, s39
	s_cmp_ge_u32 s39, s38
	s_cbranch_scc1 .LBB0_69
	v_lshlrev_b32_e32 v8, 1, v64
	v_mov_b32_e32 v9, v3
	s_add_u32 s62, s64, 0x3f900000
	v_lshlrev_b32_e32 v2, 2, v56
	v_lshl_add_u64 v[10:11], s[44:45], 0, v[8:9]
	s_mov_b64 s[44:45], 0x7c00000
	v_lshl_add_u64 v[14:15], s[42:43], 0, v[8:9]
	s_mov_b64 s[42:43], 0x5c00000
	v_lshl_add_u64 v[18:19], s[40:41], 0, v[8:9]
	s_mov_b64 s[40:41], 0x1000000
	s_addc_u32 s63, s65, 0
	v_lshl_add_u64 v[4:5], s[56:57], 0, v[2:3]
	v_lshl_add_u64 v[6:7], s[54:55], 0, v[2:3]
	v_lshl_add_u64 v[10:11], v[10:11], 0, s[44:45]
	v_lshl_add_u64 v[12:13], s[46:47], 0, v[2:3]
	v_lshl_add_u64 v[14:15], v[14:15], 0, s[42:43]
	v_lshl_add_u64 v[16:17], s[68:69], 0, v[2:3]
	v_lshl_add_u64 v[18:19], v[18:19], 0, s[40:41]
	s_branch .LBB0_74

.LBB0_319:
	s_add_i32 s14, s18, 0x8d
	s_cmpk_gt_i32 s18, 0x322
	s_mov_b32 s18, s14
	s_cbranch_scc1 .LBB0_335

.LBB0_327:
	s_andn2_b64 vcc, exec, s[16:17]
	s_cbranch_vccnz .LBB0_329
	s_add_i32 s16, s20, 0xffffe500
	s_lshr_b32 s16, s16, 2
	s_and_b32 s17, s16, 0x3fffffc0
	s_lshl_b32 s16, s20, 5
	s_and_b32 s16, s16, 0x1fe0
	v_add_u32_e32 v20, s17, v1
	s_lshl_b32 s90, s16, 2
	v_ashrrev_i32_e32 v21, 31, v20
	v_lshl_add_u64 v[22:23], v[6:7], 0, s[90:91]
	v_lshlrev_b64 v[20:21], 15, v[20:21]
	v_lshl_add_u64 v[20:21], v[22:23], 0, v[20:21]
	v_add_co_u32_e32 v22, vcc, 0x10000, v20
	global_load_dword v9, v[20:21], off nt
	s_nop 0
	v_addc_co_u32_e32 v23, vcc, 0, v21, vcc
	global_load_dword v18, v[22:23], off nt
	v_add_co_u32_e32 v22, vcc, 0x20000, v20
	s_lshl_b32 s90, s17, 1
	s_nop 0
	v_addc_co_u32_e32 v23, vcc, 0, v21, vcc
	global_load_dword v30, v[22:23], off nt
	v_add_co_u32_e32 v22, vcc, 0x30000, v20
	s_nop 1
	v_addc_co_u32_e32 v23, vcc, 0, v21, vcc
	global_load_dword v31, v[22:23], off nt
	v_add_co_u32_e32 v22, vcc, 0x40000, v20
	s_nop 1
	v_addc_co_u32_e32 v23, vcc, 0, v21, vcc
	global_load_dword v32, v[22:23], off nt
	v_add_co_u32_e32 v22, vcc, 0x50000, v20
	s_nop 1
	v_addc_co_u32_e32 v23, vcc, 0, v21, vcc
	global_load_dword v33, v[22:23], off nt
	v_add_co_u32_e32 v22, vcc, 0x60000, v20
	s_nop 1
	v_addc_co_u32_e32 v23, vcc, 0, v21, vcc
	global_load_dword v34, v[22:23], off nt
	v_add_co_u32_e32 v22, vcc, 0x70000, v20
	s_nop 1
	v_addc_co_u32_e32 v23, vcc, 0, v21, vcc
	global_load_dword v35, v[22:23], off nt
	v_add_co_u32_e32 v22, vcc, 0x80000, v20
	s_nop 1
	v_addc_co_u32_e32 v23, vcc, 0, v21, vcc
	global_load_dword v36, v[22:23], off nt
	v_add_co_u32_e32 v22, vcc, 0x90000, v20
	s_nop 1
	v_addc_co_u32_e32 v23, vcc, 0, v21, vcc
	global_load_dword v37, v[22:23], off nt
	v_add_co_u32_e32 v22, vcc, 0xa0000, v20
	s_nop 1
	v_addc_co_u32_e32 v23, vcc, 0, v21, vcc
	global_load_dword v38, v[22:23], off nt
	v_add_co_u32_e32 v22, vcc, 0xb0000, v20
	s_nop 1
	v_addc_co_u32_e32 v23, vcc, 0, v21, vcc
	global_load_dword v39, v[22:23], off nt
	v_add_co_u32_e32 v22, vcc, 0xc0000, v20
	s_nop 1
	v_addc_co_u32_e32 v23, vcc, 0, v21, vcc
	global_load_dword v40, v[22:23], off nt
	v_add_co_u32_e32 v22, vcc, 0xd0000, v20
	s_nop 1
	v_addc_co_u32_e32 v23, vcc, 0, v21, vcc
	global_load_dword v41, v[22:23], off nt
	v_add_co_u32_e32 v22, vcc, 0xe0000, v20
	s_nop 1
	v_addc_co_u32_e32 v23, vcc, 0, v21, vcc
	global_load_dword v42, v[22:23], off nt
	v_add_co_u32_e32 v22, vcc, 0xf0000, v20
	s_nop 1
	v_addc_co_u32_e32 v23, vcc, 0, v21, vcc
	global_load_dword v43, v[22:23], off nt
	v_add_co_u32_e32 v22, vcc, 0x100000, v20
	s_nop 1
	v_addc_co_u32_e32 v23, vcc, 0, v21, vcc
	global_load_dword v44, v[22:23], off nt
	v_add_co_u32_e32 v22, vcc, 0x110000, v20
	s_nop 1
	v_addc_co_u32_e32 v23, vcc, 0, v21, vcc
	global_load_dword v45, v[22:23], off nt
	v_add_co_u32_e32 v22, vcc, 0x120000, v20
	s_nop 1
	v_addc_co_u32_e32 v23, vcc, 0, v21, vcc
	global_load_dword v46, v[22:23], off nt
	v_add_co_u32_e32 v22, vcc, 0x130000, v20
	s_nop 1
	v_addc_co_u32_e32 v23, vcc, 0, v21, vcc
	global_load_dword v47, v[22:23], off nt
	v_add_co_u32_e32 v22, vcc, 0x140000, v20
	s_nop 1
	v_addc_co_u32_e32 v23, vcc, 0, v21, vcc
	global_load_dword v48, v[22:23], off nt
	v_add_co_u32_e32 v22, vcc, 0x150000, v20
	s_nop 1
	v_addc_co_u32_e32 v23, vcc, 0, v21, vcc
	global_load_dword v49, v[22:23], off nt
	v_add_co_u32_e32 v22, vcc, 0x160000, v20
	s_nop 1
	v_addc_co_u32_e32 v23, vcc, 0, v21, vcc
	global_load_dword v50, v[22:23], off nt
	v_add_co_u32_e32 v22, vcc, 0x170000, v20
	s_nop 1
	v_addc_co_u32_e32 v23, vcc, 0, v21, vcc
	global_load_dword v51, v[22:23], off nt
	v_add_co_u32_e32 v22, vcc, 0x180000, v20
	s_nop 1
	v_addc_co_u32_e32 v23, vcc, 0, v21, vcc
	global_load_dword v52, v[22:23], off nt
	v_add_co_u32_e32 v22, vcc, 0x190000, v20
	s_nop 1
	v_addc_co_u32_e32 v23, vcc, 0, v21, vcc
	global_load_dword v53, v[22:23], off nt
	v_add_co_u32_e32 v22, vcc, 0x1a0000, v20
	s_nop 1
	v_addc_co_u32_e32 v23, vcc, 0, v21, vcc
	global_load_dword v54, v[22:23], off nt
	v_add_co_u32_e32 v22, vcc, 0x1b0000, v20
	s_nop 1
	v_addc_co_u32_e32 v23, vcc, 0, v21, vcc
	global_load_dword v55, v[22:23], off nt
	v_add_co_u32_e32 v22, vcc, 0x1c0000, v20
	s_nop 1
	v_addc_co_u32_e32 v23, vcc, 0, v21, vcc
	global_load_dword v56, v[22:23], off nt
	v_add_co_u32_e32 v22, vcc, 0x1d0000, v20
	s_nop 1
	v_addc_co_u32_e32 v23, vcc, 0, v21, vcc
	global_load_dword v57, v[22:23], off nt
	v_add_co_u32_e32 v22, vcc, 0x1e0000, v20
	s_nop 1
	v_addc_co_u32_e32 v23, vcc, 0, v21, vcc
	v_add_co_u32_e32 v20, vcc, 0x1f0000, v20
	global_load_dword v22, v[22:23], off nt
	s_nop 0
	v_addc_co_u32_e32 v21, vcc, 0, v21, vcc
	global_load_dword v20, v[20:21], off nt
	s_waitcnt vmcnt(0)
	ds_write2_b32 v24, v9, v18 offset1:66
	ds_write2_b32 v24, v30, v31 offset0:132 offset1:198
	v_add_u32_e32 v9, 0x400, v24
	ds_write2_b32 v9, v32, v33 offset0:8 offset1:74
	ds_write2_b32 v9, v34, v35 offset0:140 offset1:206
	v_add_u32_e32 v9, 0x800, v24
	ds_write2_b32 v9, v36, v37 offset0:16 offset1:82
	ds_write2_b32 v9, v38, v39 offset0:148 offset1:214
	v_add_u32_e32 v9, 0xc00, v24
	ds_write2_b32 v9, v40, v41 offset0:24 offset1:90
	ds_write2_b32 v9, v42, v43 offset0:156 offset1:222
	v_add_u32_e32 v9, 0x1000, v24
	ds_write2_b32 v9, v44, v45 offset0:32 offset1:98
	ds_write2_b32 v9, v46, v47 offset0:164 offset1:230
	v_add_u32_e32 v9, 0x1400, v24
	ds_write2_b32 v9, v48, v49 offset0:40 offset1:106
	ds_write2_b32 v9, v50, v51 offset0:172 offset1:238
	v_add_u32_e32 v9, 0x1800, v24
	ds_write2_b32 v9, v52, v53 offset0:48 offset1:114
	ds_write2_b32 v9, v54, v55 offset0:180 offset1:246
	v_add_u32_e32 v9, 0x1c00, v24
	ds_write2_b32 v9, v56, v57 offset0:56 offset1:122
	ds_write2_b32 v9, v22, v20 offset0:188 offset1:254
	s_waitcnt lgkmcnt(0)
	ds_read2_b32 v[22:23], v26 offset0:33 offset1:41
	ds_read2_b32 v[34:35], v26 offset1:8
	ds_read2_b32 v[36:37], v26 offset0:66 offset1:74
	ds_read2_b32 v[38:39], v26 offset0:99 offset1:107
	ds_read2_b32 v[40:41], v26 offset0:132 offset1:140
	ds_read2_b32 v[42:43], v26 offset0:165 offset1:173
	ds_read2_b32 v[44:45], v26 offset0:198 offset1:206
	ds_read2_b32 v[46:47], v26 offset0:231 offset1:239
	s_waitcnt lgkmcnt(7)
	v_bfe_u32 v18, v22, 16, 1
	s_waitcnt lgkmcnt(6)
	v_bfe_u32 v9, v34, 16, 1
	v_add3_u32 v9, v34, v9, s79
	v_lshrrev_b32_e32 v9, 16, v9
	v_add3_u32 v18, v22, v18, s79
	v_and_or_b32 v30, v18, s80, v9
	s_waitcnt lgkmcnt(5)
	v_bfe_u32 v9, v36, 16, 1
	v_add3_u32 v9, v36, v9, s79
	s_waitcnt lgkmcnt(4)
	v_bfe_u32 v18, v38, 16, 1
	v_lshrrev_b32_e32 v9, 16, v9
	v_add3_u32 v18, v38, v18, s79
	v_and_or_b32 v31, v18, s80, v9
	s_waitcnt lgkmcnt(3)
	v_bfe_u32 v9, v40, 16, 1
	v_add3_u32 v9, v40, v9, s79
	s_waitcnt lgkmcnt(2)
	v_bfe_u32 v18, v42, 16, 1
	v_lshrrev_b32_e32 v9, 16, v9
	v_add3_u32 v18, v42, v18, s79
	v_and_or_b32 v32, v18, s80, v9
	s_waitcnt lgkmcnt(1)
	v_bfe_u32 v9, v44, 16, 1
	v_add3_u32 v9, v44, v9, s79
	s_waitcnt lgkmcnt(0)
	v_bfe_u32 v18, v46, 16, 1
	v_lshrrev_b32_e32 v9, 16, v9
	v_add3_u32 v18, v46, v18, s79
	v_add_u32_e32 v48, s16, v25
	v_and_or_b32 v33, v18, s80, v9
	v_ashrrev_i32_e32 v49, 31, v48
	v_bfe_u32 v9, v35, 16, 1
	v_lshl_add_u64 v[20:21], v[10:11], 0, s[90:91]
	s_lshl_b32 s100, s90, 8
	s_lshr_b32 s101, s16, 8
	s_lshl_b32 s101, s101, 20
	s_add_i32 s100, s100, s101
	s_bfe_u32 s101, s16, 0x10007
	s_lshl_b32 s101, s101, 14
	s_add_i32 s100, s100, s101
	s_bfe_u32 s101, s16, 0x20005
	s_lshl_b32 s101, s101, 12
	s_add_i32 s100, s100, s101
	v_mbcnt_lo_u32_b32 v61, -1, 0
	v_mbcnt_hi_u32_b32 v61, -1, v61
	v_lshrrev_b32_e32 v62, 5, v61
	v_lshlrev_b32_e32 v62, 11, v62
	v_bfe_u32 v64, v61, 2, 1
	v_lshl_or_b32 v62, v64, 10, v62
	v_bfe_u32 v64, v61, 3, 2
	v_lshl_or_b32 v62, v64, 6, v62
	v_and_b32_e32 v64, 3, v61
	v_lshl_or_b32 v62, v64, 4, v62
	v_add_u32_e32 v62, s100, v62
	v_xor_b32_e32 v64, 32, v62
	v_mov_b32_e32 v63, v19
	v_mov_b32_e32 v65, v19
	v_sub_u32_e32 v68, 0, v8
	v_ashrrev_i32_e32 v69, 31, v68
	v_lshl_add_u64 v[66:67], v[10:11], 0, v[68:69]
	v_lshl_add_u64 v[68:69], v[66:67], 0, v[62:63]
	v_lshl_add_u64 v[66:67], v[66:67], 0, v[64:65]
	v_lshlrev_b64 v[48:49], 12, v[48:49]
	v_add3_u32 v9, v35, v9, s79
	v_bfe_u32 v18, v23, 16, 1
	v_lshl_add_u64 v[48:49], v[20:21], 0, v[48:49]
	v_lshrrev_b32_e32 v9, 16, v9
	v_add3_u32 v18, v23, v18, s79
	global_store_dwordx4 v[68:69], v[30:33], off nt
	v_add_u32_e32 v22, s16, v27
	v_ashrrev_i32_e32 v23, 31, v22
	v_and_or_b32 v30, v18, s80, v9
	v_bfe_u32 v9, v37, 16, 1
	v_add3_u32 v9, v37, v9, s79
	v_bfe_u32 v18, v39, 16, 1
	v_lshrrev_b32_e32 v9, 16, v9
	v_add3_u32 v18, v39, v18, s79
	v_and_or_b32 v31, v18, s80, v9
	v_bfe_u32 v9, v41, 16, 1
	v_add3_u32 v9, v41, v9, s79
	v_bfe_u32 v18, v43, 16, 1
	v_lshrrev_b32_e32 v9, 16, v9
	v_add3_u32 v18, v43, v18, s79
	v_and_or_b32 v32, v18, s80, v9
	v_bfe_u32 v9, v45, 16, 1
	v_add3_u32 v9, v45, v9, s79
	v_bfe_u32 v18, v47, 16, 1
	v_lshrrev_b32_e32 v9, 16, v9
	v_add3_u32 v18, v47, v18, s79
	v_lshlrev_b64 v[22:23], 12, v[22:23]
	v_and_or_b32 v33, v18, s80, v9
	v_lshl_add_u64 v[22:23], v[20:21], 0, v[22:23]
	global_store_dwordx4 v[68:69], v[30:33], off offset:256 nt
	ds_read2_b32 v[22:23], v26 offset0:49 offset1:57
	ds_read2_b32 v[34:35], v26 offset0:16 offset1:24
	ds_read2_b32 v[36:37], v26 offset0:82 offset1:90
	ds_read2_b32 v[38:39], v26 offset0:115 offset1:123
	ds_read2_b32 v[40:41], v26 offset0:148 offset1:156
	ds_read2_b32 v[42:43], v26 offset0:181 offset1:189
	ds_read2_b32 v[44:45], v26 offset0:214 offset1:222
	ds_read2_b32 v[46:47], v26 offset0:247 offset1:255
	s_waitcnt lgkmcnt(7)
	v_bfe_u32 v18, v22, 16, 1
	s_waitcnt lgkmcnt(6)
	v_bfe_u32 v9, v34, 16, 1
	v_add3_u32 v9, v34, v9, s79
	v_lshrrev_b32_e32 v9, 16, v9
	v_add3_u32 v18, v22, v18, s79
	v_and_or_b32 v30, v18, s80, v9
	s_waitcnt lgkmcnt(5)
	v_bfe_u32 v9, v36, 16, 1
	v_add3_u32 v9, v36, v9, s79
	s_waitcnt lgkmcnt(4)
	v_bfe_u32 v18, v38, 16, 1
	v_lshrrev_b32_e32 v9, 16, v9
	v_add3_u32 v18, v38, v18, s79
	v_and_or_b32 v31, v18, s80, v9
	s_waitcnt lgkmcnt(3)
	v_bfe_u32 v9, v40, 16, 1
	v_add3_u32 v9, v40, v9, s79
	s_waitcnt lgkmcnt(2)
	v_bfe_u32 v18, v42, 16, 1
	v_lshrrev_b32_e32 v9, 16, v9
	v_add3_u32 v18, v42, v18, s79
	v_and_or_b32 v32, v18, s80, v9
	s_waitcnt lgkmcnt(1)
	v_bfe_u32 v9, v44, 16, 1
	v_add3_u32 v9, v44, v9, s79
	s_waitcnt lgkmcnt(0)
	v_bfe_u32 v18, v46, 16, 1
	v_lshrrev_b32_e32 v9, 16, v9
	v_add3_u32 v18, v46, v18, s79
	v_add_u32_e32 v48, s16, v28
	v_and_or_b32 v33, v18, s80, v9
	v_ashrrev_i32_e32 v49, 31, v48
	v_bfe_u32 v9, v35, 16, 1
	v_lshlrev_b64 v[48:49], 12, v[48:49]
	v_add3_u32 v9, v35, v9, s79
	v_bfe_u32 v18, v23, 16, 1
	v_lshl_add_u64 v[48:49], v[20:21], 0, v[48:49]
	v_lshrrev_b32_e32 v9, 16, v9
	v_add3_u32 v18, v23, v18, s79
	global_store_dwordx4 v[66:67], v[30:33], off offset:512 nt
	v_add_u32_e32 v22, s16, v29
	v_ashrrev_i32_e32 v23, 31, v22
	v_and_or_b32 v30, v18, s80, v9
	v_bfe_u32 v9, v37, 16, 1
	v_add3_u32 v9, v37, v9, s79
	v_bfe_u32 v18, v39, 16, 1
	v_lshrrev_b32_e32 v9, 16, v9
	v_add3_u32 v18, v39, v18, s79
	v_and_or_b32 v31, v18, s80, v9
	v_bfe_u32 v9, v41, 16, 1
	v_add3_u32 v9, v41, v9, s79
	v_bfe_u32 v18, v43, 16, 1
	v_lshrrev_b32_e32 v9, 16, v9
	v_add3_u32 v18, v43, v18, s79
	v_and_or_b32 v32, v18, s80, v9
	v_bfe_u32 v9, v45, 16, 1
	v_add3_u32 v9, v45, v9, s79
	v_bfe_u32 v18, v47, 16, 1
	v_lshrrev_b32_e32 v9, 16, v9
	v_add3_u32 v18, v47, v18, s79
	v_lshlrev_b64 v[22:23], 12, v[22:23]
	v_and_or_b32 v33, v18, s80, v9
	v_lshl_add_u64 v[20:21], v[20:21], 0, v[22:23]
	global_store_dwordx4 v[66:67], v[30:33], off offset:768 nt
	s_waitcnt lgkmcnt(0)

.LBB0_1746:
	s_andn2_b64 vcc, exec, s[0:1]
	s_cbranch_vccnz .LBB0_1837
	v_readlane_b32 s6, v254, 14
	s_add_i32 s4, s6, 8
	s_cmp_le_i32 s76, s4
	s_cselect_b64 s[0:1], -1, 0
	s_cmp_lt_i32 s4, s77
	s_cselect_b64 s[4:5], -1, 0
	s_and_b64 s[4:5], s[0:1], s[4:5]
	s_lshl_b32 s0, s88, 24
	s_cmp_eq_u32 s88, 3
	s_cselect_b32 s39, 1, 2
	s_add_i32 s38, s6, 9
	s_cmp_lt_i32 s38, s77
	s_mov_b32 s40, 0
	s_cselect_b64 s[6:7], -1, 0
	s_lshl_b32 s41, s0, 1
	s_branch .LBB0_1751

.LBB0_1751:
	s_andn2_b64 vcc, exec, s[4:5]
	s_cbranch_vccnz .LBB0_1750
	v_readlane_b32 s42, v250, 6
	v_mov_b32_e32 v146, v164
	v_readlane_b32 s0, v250, 14
	v_mov_b32_e32 v1, v0
	s_mov_b64 s[0:1], s[30:31]
	s_mov_b64 s[0:1], s[30:31]
	s_mov_b64 s[0:1], s[30:31]
	s_mov_b64 s[0:1], s[30:31]
	s_mov_b64 s[0:1], s[30:31]
	s_mov_b64 s[0:1], s[30:31]
	s_mov_b64 s[8:9], s[30:31]
	s_mov_b64 s[0:1], s[30:31]
	s_mov_b64 s[10:11], s[30:31]
	s_mov_b64 s[0:1], s[30:31]
	s_mov_b64 s[0:1], s[30:31]
	s_mov_b64 s[0:1], s[30:31]
	s_mov_b64 s[12:13], s[30:31]
	s_mov_b64 s[12:13], s[30:31]
	s_mov_b64 s[12:13], s[30:31]
	s_mov_b64 s[12:13], s[30:31]
	s_mov_b64 s[12:13], s[30:31]
	s_mov_b64 s[12:13], s[30:31]
	s_waitcnt vmcnt(0) lgkmcnt(0)
	v_mov_b32_e32 v10, v0
	v_readlane_b32 s12, v253, 58
	v_readlane_b32 s13, v253, 59
	s_andn2_b64 vcc, exec, s[12:13]
	v_readfirstlane_b32 s12, v10
	s_cbranch_vccnz .LBB0_1768
	v_lshlrev_b32_e32 v1, 4, v10
	v_add_u32_e32 v2, 0x2000, v1
	v_ashrrev_i32_e32 v3, 31, v2
	v_lshrrev_b32_e32 v3, 22, v3
	v_add_u32_e32 v3, v2, v3
	v_ashrrev_i32_e32 v11, 10, v3
	v_mul_i32_i24_e32 v3, 0x400, v11
	v_sub_u32_e32 v2, v2, v3
	v_lshrrev_b32_e32 v3, 4, v2
	v_bitop3_b32 v2, v3, v2, 32 bitop3:0x6c
	v_ashrrev_i32_e32 v3, 31, v2
	s_add_u32 s43, s10, 0x17c00000
	v_lshrrev_b32_e32 v3, 26, v3
	s_addc_u32 s44, s11, 0
	v_add_u32_e32 v3, v2, v3
	v_lshlrev_b32_e32 v4, 3, v11
	s_add_u32 s8, s8, s41
	v_ashrrev_i32_e32 v12, 6, v3
	v_and_b32_e32 v4, -16, v4
	s_addc_u32 s9, s9, 0
	v_add_u32_e32 v4, v12, v4
	s_add_u32 s45, s8, 0x7c00000
	v_and_b32_e32 v5, 3, v12
	s_mov_b32 s8, 0xfffe0
	v_lshrrev_b32_e32 v6, 2, v4
	v_lshlrev_b32_e32 v7, 1, v4
	v_and_b32_e32 v3, 0xc0, v3
	v_and_or_b32 v5, v4, s8, v5
	v_and_b32_e32 v6, 4, v6
	v_and_b32_e32 v7, 24, v7
	v_sub_u32_e32 v2, v2, v3
	v_or3_b32 v5, v5, v6, v7
	v_lshlrev_b32_e32 v6, 5, v11
	v_ashrrev_i16_sdwa v2, v210, sext(v2) dst_sel:DWORD dst_unused:UNUSED_PAD src0_sel:DWORD src1_sel:BYTE_0
	v_and_b32_e32 v6, 32, v6
	v_bfe_i32 v13, v2, 0, 16
	v_add_lshl_u32 v2, v6, v13, 1
	v_lshlrev_b32_e32 v132, 4, v10
	v_add_u32_e32 v132, 0x2000, v132
	v_lshl_add_u32 v134, v4, 12, v2
	v_bfe_i32 v2, v10, 27, 1
	v_lshrrev_b32_e32 v2, 22, v2
	v_add_u32_e32 v2, v1, v2
	v_and_b32_e32 v2, 0xfffffc00, v2
	v_sub_u32_e32 v1, v1, v2
	v_lshrrev_b32_e32 v2, 4, v1
	v_ashrrev_i32_e32 v3, 31, v10
	v_bitop3_b32 v1, v2, v1, 32 bitop3:0x6c
	v_lshrrev_b32_e32 v3, 26, v3
	v_ashrrev_i32_e32 v2, 31, v1
	v_add_u32_e32 v3, v10, v3
	v_lshrrev_b32_e32 v2, 26, v2
	v_ashrrev_i32_e32 v15, 6, v3
	v_add_u32_e32 v2, v1, v2
	v_lshlrev_b32_e32 v3, 3, v15
	v_ashrrev_i32_e32 v14, 6, v2
	v_and_b32_e32 v3, -16, v3
	v_add_u32_e32 v3, v14, v3
	v_and_b32_e32 v4, 3, v14
	v_lshrrev_b32_e32 v5, 2, v3
	v_lshlrev_b32_e32 v6, 1, v3
	v_and_b32_e32 v2, 0xc0, v2
	s_addc_u32 s46, s9, 0
	s_ashr_i32 s13, s12, 6
	v_and_or_b32 v4, v3, s8, v4
	v_and_b32_e32 v5, 4, v5
	v_and_b32_e32 v6, 24, v6
	v_sub_u32_e32 v1, v1, v2
	s_ashr_i32 s14, s12, 8
	s_lshl_b32 s47, s13, 10
	v_or3_b32 v4, v4, v5, v6
	v_lshlrev_b32_e32 v5, 5, v15
	v_ashrrev_i16_sdwa v1, v210, sext(v1) dst_sel:DWORD dst_unused:UNUSED_PAD src0_sel:DWORD src1_sel:BYTE_0
	v_readlane_b32 s8, v252, 39
	v_and_b32_e32 v5, 32, v5
	v_bfe_i32 v16, v1, 0, 16
	v_readlane_b32 s9, v252, 40
	s_add_u32 s22, s45, s8
	v_add_lshl_u32 v1, v5, v16, 1
	s_addc_u32 s23, s46, s9
	s_sub_u32 s100, s22, s30
	s_and_b32 s101, s100, 0xf80
	s_lshl_b32 s101, s101, 8
	s_and_b32 s100, s100, 0xfff00000
	s_or_b32 s100, s100, s101
	s_add_u32 s100, s30, s100
	s_addc_u32 s101, s31, 0
	s_add_i32 s48, s47, 0
	v_lshlrev_b32_e32 v136, 4, v10
	s_add_i32 m0, s48, 0x10000
	v_lshl_add_u32 v138, v3, 12, v1
	global_load_lds_dwordx4 v136, s[100:101]
	s_add_i32 m0, s48, 0x12000
	s_add_u32 s8, s100, 0x4000
	global_load_lds_dwordx4 v132, s[100:101]
	s_addc_u32 s9, s101, 0
	s_add_i32 m0, s48, 0x14000
	v_mov_b32_e32 v137, v19
	global_load_lds_dwordx4 v136, s[8:9]
	s_add_i32 m0, s48, 0x16000
	v_mov_b32_e32 v133, v19
	global_load_lds_dwordx4 v132, s[8:9]
	s_add_u32 s100, s100, 0x7f80
	s_addc_u32 s101, s101, 0
	v_readlane_b32 s8, v252, 43
	v_readlane_b32 s9, v252, 44
	s_add_u32 s24, s43, s8
	s_addc_u32 s25, s44, s9
	s_add_i32 s49, s48, 0x2000
	s_mov_b32 m0, s48
	s_add_u32 s8, s24, 0x80000
	global_load_lds_dwordx4 v138, s[24:25]
	s_mov_b32 m0, s49
	s_addc_u32 s9, s25, 0
	s_add_i32 s50, s48, 0x4000
	global_load_lds_dwordx4 v134, s[24:25]
	s_mov_b32 m0, s50
	s_add_i32 s51, s48, 0x6000
	global_load_lds_dwordx4 v138, s[8:9]
	s_mov_b32 m0, s51
	v_mov_b32_e32 v139, v19
	global_load_lds_dwordx4 v134, s[8:9]
	v_mov_b32_e32 v135, v19
	s_cmp_eq_u32 s14, 1
	v_lshl_add_u64 v[8:9], s[100:101], 0, v[136:137]
	v_lshl_add_u64 v[6:7], s[100:101], 0, v[132:133]
	v_lshl_add_u64 v[2:3], s[24:25], 0, v[138:139]
	s_cselect_b64 s[8:9], -1, 0
	s_cmp_lg_u32 s14, 1
	v_lshl_add_u64 v[4:5], s[24:25], 0, v[134:135]
	s_cbranch_scc1 .LBB0_1755
	s_barrier
.LBB0_1755:
	s_add_u32 s10, s0, 0x37300000
	s_addc_u32 s11, s1, 0
	s_mov_b64 s[0:1], 0x80
	s_lshl_b32 s15, s13, 5
	s_add_i32 m0, s48, 0x18000
	v_lshl_add_u64 v[8:9], v[8:9], 0, s[0:1]
	s_and_b32 s53, s15, 0x60
	s_waitcnt vmcnt(2)
	s_barrier
	global_load_lds_dwordx4 v[8:9], off
	v_lshl_add_u64 v[6:7], v[6:7], 0, s[0:1]
	s_add_i32 m0, s48, 0x1a000
	s_add_i32 s54, s48, 0x8000
	s_lshl_b32 s52, s14, 6
	s_lshl_b32 s14, s14, 13
	s_lshl_b32 s13, s53, 7
	global_load_lds_dwordx4 v[6:7], off
	v_lshl_add_u64 v[2:3], v[2:3], 0, s[0:1]
	s_mov_b32 m0, s54
	s_add_i32 s55, s48, 0xa000
	global_load_lds_dwordx4 v[2:3], off
	v_lshl_add_u64 v[2:3], v[4:5], 0, s[0:1]
	s_add_u32 s0, s100, 0x4080
	s_mov_b32 m0, s55
	s_addc_u32 s1, s101, 0
	global_load_lds_dwordx4 v[2:3], off
	s_add_i32 m0, s48, 0x1c000
	v_lshl_add_u64 v[2:3], s[0:1], 0, v[136:137]
	global_load_lds_dwordx4 v[2:3], off
	v_lshl_add_u64 v[2:3], s[0:1], 0, v[132:133]
	s_add_i32 m0, s48, 0x1e000
	v_and_b32_e32 v1, 15, v10
	global_load_lds_dwordx4 v[2:3], off
	v_lshrrev_b32_e32 v2, 1, v10
	v_and_b32_e32 v2, 24, v2
	v_lshlrev_b32_e32 v3, 1, v2
	v_lshlrev_b32_e32 v4, 2, v10
	v_lshl_or_b32 v3, v1, 6, v3
	v_and_b32_e32 v4, 32, v4
	v_bitop3_b32 v5, v3, s14, v4 bitop3:0xde
	v_bitop3_b32 v147, v3, s13, v4 bitop3:0xde
	v_lshlrev_b32_e32 v3, 15, v11
	v_and_b32_e32 v3, 0xffff0000, v3
	v_lshl_add_u32 v3, v12, 12, v3
	v_and_b32_e32 v4, 1, v11
	v_lshl_or_b32 v3, v4, 6, v3
	v_lshl_add_u32 v140, v13, 1, v3
	v_lshlrev_b32_e32 v3, 15, v15
	v_and_b32_e32 v3, 0xffff0000, v3
	s_waitcnt vmcnt(6)
	v_lshl_add_u32 v3, v14, 12, v3
	v_and_b32_e32 v4, 1, v15
	s_cmpk_lt_u32 s12, 0x100
	v_and_or_b32 v2, s15, 32, v2
	v_lshl_or_b32 v3, v4, 6, v3
	v_readlane_b32 s0, v252, 41
	s_cselect_b64 s[12:13], -1, 0
	v_mov_b32_e32 v141, v19
	v_lshl_add_u32 v142, v16, 1, v3
	v_mov_b32_e32 v143, v19
	s_mov_b32 s56, 0
	v_add_u32_e32 v148, 0, v5
	v_lshlrev_b32_e32 v144, 1, v2
	v_readlane_b32 s57, v252, 38
	s_mov_b32 s58, s0
	s_barrier
	v_readlane_b32 s1, v252, 42
	s_branch .LBB0_1758

.LBB0_1761:
	s_add_u32 s24, s22, 0xfff80080
	s_addc_u32 s25, s23, -1
	s_cmp_eq_u32 s63, 28
	s_cselect_b32 s27, s17, s25
	s_cselect_b32 s26, s59, s24
	v_add_u32_e32 v18, s67, v147
	s_cselect_b32 s25, s15, s62
	s_cselect_b32 s24, s60, s61
	s_sub_u32 s66, s24, s30
	s_and_b32 s64, s66, 0xf80
	s_lshl_b32 s64, s64, 8
	s_and_b32 s66, s66, 0xfff00000
	s_or_b32 s66, s66, s64
	s_add_u32 s24, s30, s66
	s_addc_u32 s25, s31, 0
	ds_read_b128 v[150:153], v18
	ds_read_b128 v[154:157], v18 offset:1024
	ds_read_b128 v[158:161], v18 offset:2048
	ds_read_b128 v[170:173], v18 offset:3072
	v_add_u32_e32 v18, 0x14000, v147
	ds_read_b128 v[174:177], v18
	ds_read_b128 v[178:181], v18 offset:1024
	ds_read_b128 v[182:185], v18 offset:2048
	ds_read_b128 v[186:189], v18 offset:3072
	s_add_i32 m0, s48, 0xc000
	ds_read_b128 v[190:193], v148
	ds_read_b128 v[194:197], v148 offset:1024
	ds_read_b128 v[198:201], v148 offset:2048
	ds_read_b128 v[202:205], v148 offset:3072
	ds_read_b128 v[206:209], v148 offset:4096
	ds_read_b128 v[220:223], v148 offset:5120
	ds_read_b128 v[224:227], v148 offset:6144
	ds_read_b128 v[228:231], v148 offset:7168
	global_load_lds_dwordx4 v142, s[22:23]
	s_add_i32 m0, s48, 0xe000
	s_nop 0
	global_load_lds_dwordx4 v140, s[22:23]
	s_waitcnt vmcnt(8)
	s_waitcnt lgkmcnt(0)
	s_barrier
	s_setprio 1
	s_waitcnt lgkmcnt(0)
	v_mfma_f32_16x16x32_bf16 v[128:131], v[150:153], v[190:193], v[128:131]
	v_mfma_f32_16x16x32_bf16 v[124:127], v[158:161], v[190:193], v[124:127]
	v_mfma_f32_16x16x32_bf16 v[112:115], v[150:153], v[198:201], v[112:115]
	v_mfma_f32_16x16x32_bf16 v[108:111], v[158:161], v[198:201], v[108:111]
	v_mfma_f32_16x16x32_bf16 v[96:99], v[150:153], v[206:209], v[96:99]
	v_mfma_f32_16x16x32_bf16 v[92:95], v[158:161], v[206:209], v[92:95]
	v_mfma_f32_16x16x32_bf16 v[80:83], v[150:153], v[224:227], v[80:83]
	v_mfma_f32_16x16x32_bf16 v[76:79], v[158:161], v[224:227], v[76:79]
	v_mfma_f32_16x16x32_bf16 v[128:131], v[154:157], v[194:197], v[128:131]
	v_mfma_f32_16x16x32_bf16 v[124:127], v[170:173], v[194:197], v[124:127]
	v_mfma_f32_16x16x32_bf16 v[112:115], v[154:157], v[202:205], v[112:115]
	v_mfma_f32_16x16x32_bf16 v[108:111], v[170:173], v[202:205], v[108:111]
	v_mfma_f32_16x16x32_bf16 v[96:99], v[154:157], v[220:223], v[96:99]
	v_mfma_f32_16x16x32_bf16 v[92:95], v[170:173], v[220:223], v[92:95]
	v_mfma_f32_16x16x32_bf16 v[80:83], v[154:157], v[228:231], v[80:83]
	v_mfma_f32_16x16x32_bf16 v[76:79], v[170:173], v[228:231], v[76:79]
	s_setprio 0
	s_setprio 1
	v_mfma_f32_16x16x32_bf16 v[120:123], v[174:177], v[190:193], v[120:123]
	v_mfma_f32_16x16x32_bf16 v[116:119], v[182:185], v[190:193], v[116:119]
	v_mfma_f32_16x16x32_bf16 v[104:107], v[174:177], v[198:201], v[104:107]
	v_mfma_f32_16x16x32_bf16 v[100:103], v[182:185], v[198:201], v[100:103]
	v_mfma_f32_16x16x32_bf16 v[88:91], v[174:177], v[206:209], v[88:91]
	v_mfma_f32_16x16x32_bf16 v[84:87], v[182:185], v[206:209], v[84:87]
	v_mfma_f32_16x16x32_bf16 v[72:75], v[174:177], v[224:227], v[72:75]
	v_mfma_f32_16x16x32_bf16 v[68:71], v[182:185], v[224:227], v[68:71]
	v_mfma_f32_16x16x32_bf16 v[120:123], v[178:181], v[194:197], v[120:123]
	v_mfma_f32_16x16x32_bf16 v[116:119], v[186:189], v[194:197], v[116:119]
	v_mfma_f32_16x16x32_bf16 v[104:107], v[178:181], v[202:205], v[104:107]
	v_mfma_f32_16x16x32_bf16 v[100:103], v[186:189], v[202:205], v[100:103]
	v_mfma_f32_16x16x32_bf16 v[88:91], v[178:181], v[220:223], v[88:91]
	v_mfma_f32_16x16x32_bf16 v[84:87], v[186:189], v[220:223], v[84:87]
	v_mfma_f32_16x16x32_bf16 v[72:75], v[178:181], v[228:231], v[72:75]
	v_mfma_f32_16x16x32_bf16 v[68:71], v[186:189], v[228:231], v[68:71]
	s_setprio 0
	s_barrier
	s_add_i32 m0, s67, s47
	ds_read_b128 v[190:193], v148 offset:16384
	ds_read_b128 v[194:197], v148 offset:17408
	ds_read_b128 v[198:201], v148 offset:18432
	ds_read_b128 v[202:205], v148 offset:19456
	ds_read_b128 v[206:209], v148 offset:20480
	ds_read_b128 v[220:223], v148 offset:21504
	ds_read_b128 v[224:227], v148 offset:22528
	ds_read_b128 v[228:231], v148 offset:23552
	global_load_lds_dwordx4 v136, s[24:25]
	s_add_i32 s66, s67, s47
	s_add_i32 m0, s66, 0x2000
	s_add_u32 s64, s24, 0x4000
	s_addc_u32 s65, s25, 0
	global_load_lds_dwordx4 v132, s[24:25]
	s_add_i32 m0, s47, 0x14000
	s_nop 0
	global_load_lds_dwordx4 v136, s[64:65]
	s_add_i32 m0, s47, 0x16000
	s_nop 0
	global_load_lds_dwordx4 v132, s[64:65]
	s_mov_b32 m0, s48
	s_nop 0
	global_load_lds_dwordx4 v138, s[26:27]
	s_mov_b32 m0, s49
	s_nop 0
	global_load_lds_dwordx4 v134, s[26:27]
	s_waitcnt vmcnt(8)
	s_waitcnt lgkmcnt(0)
	s_barrier
	s_setprio 1
	s_waitcnt lgkmcnt(0)
	v_mfma_f32_16x16x32_bf16 v[64:67], v[150:153], v[190:193], v[64:67]
	v_mfma_f32_16x16x32_bf16 v[60:63], v[158:161], v[190:193], v[60:63]
	v_mfma_f32_16x16x32_bf16 v[48:51], v[150:153], v[198:201], v[48:51]
	v_mfma_f32_16x16x32_bf16 v[44:47], v[158:161], v[198:201], v[44:47]
	v_mfma_f32_16x16x32_bf16 v[32:35], v[150:153], v[206:209], v[32:35]
	v_mfma_f32_16x16x32_bf16 v[28:31], v[158:161], v[206:209], v[28:31]
	v_mfma_f32_16x16x32_bf16 v[14:17], v[150:153], v[224:227], v[14:17]
	v_mfma_f32_16x16x32_bf16 v[10:13], v[158:161], v[224:227], v[10:13]
	v_mfma_f32_16x16x32_bf16 v[64:67], v[154:157], v[194:197], v[64:67]
	v_mfma_f32_16x16x32_bf16 v[60:63], v[170:173], v[194:197], v[60:63]
	v_mfma_f32_16x16x32_bf16 v[48:51], v[154:157], v[202:205], v[48:51]
	v_mfma_f32_16x16x32_bf16 v[44:47], v[170:173], v[202:205], v[44:47]
	v_mfma_f32_16x16x32_bf16 v[32:35], v[154:157], v[220:223], v[32:35]
	v_mfma_f32_16x16x32_bf16 v[28:31], v[170:173], v[220:223], v[28:31]
	v_mfma_f32_16x16x32_bf16 v[14:17], v[154:157], v[228:231], v[14:17]
	v_mfma_f32_16x16x32_bf16 v[10:13], v[170:173], v[228:231], v[10:13]
	s_setprio 0
	s_setprio 1
	v_mfma_f32_16x16x32_bf16 v[56:59], v[174:177], v[190:193], v[56:59]
	v_mfma_f32_16x16x32_bf16 v[52:55], v[182:185], v[190:193], v[52:55]
	v_mfma_f32_16x16x32_bf16 v[40:43], v[174:177], v[198:201], v[40:43]
	v_mfma_f32_16x16x32_bf16 v[36:39], v[182:185], v[198:201], v[36:39]
	v_mfma_f32_16x16x32_bf16 v[24:27], v[174:177], v[206:209], v[24:27]
	v_mfma_f32_16x16x32_bf16 v[20:23], v[182:185], v[206:209], v[20:23]
	v_mfma_f32_16x16x32_bf16 v[6:9], v[174:177], v[224:227], v[6:9]
	v_mfma_f32_16x16x32_bf16 v[2:5], v[182:185], v[224:227], v[2:5]
	v_mfma_f32_16x16x32_bf16 v[56:59], v[178:181], v[194:197], v[56:59]
	v_mfma_f32_16x16x32_bf16 v[52:55], v[186:189], v[194:197], v[52:55]
	v_mfma_f32_16x16x32_bf16 v[40:43], v[178:181], v[202:205], v[40:43]
	v_mfma_f32_16x16x32_bf16 v[36:39], v[186:189], v[202:205], v[36:39]
	v_mfma_f32_16x16x32_bf16 v[24:27], v[178:181], v[220:223], v[24:27]
	v_mfma_f32_16x16x32_bf16 v[20:23], v[186:189], v[220:223], v[20:23]
	v_mfma_f32_16x16x32_bf16 v[6:9], v[178:181], v[228:231], v[6:9]
	v_mfma_f32_16x16x32_bf16 v[2:5], v[186:189], v[228:231], v[2:5]
	s_setprio 0
	s_barrier
	v_add_u32_e32 v18, 0x18000, v147
	ds_read_b128 v[150:153], v18
	ds_read_b128 v[154:157], v18 offset:1024
	ds_read_b128 v[158:161], v18 offset:2048
	ds_read_b128 v[170:173], v18 offset:3072
	v_add_u32_e32 v18, 0x1c000, v147
	ds_read_b128 v[174:177], v18
	ds_read_b128 v[178:181], v18 offset:1024
	ds_read_b128 v[182:185], v18 offset:2048
	ds_read_b128 v[186:189], v18 offset:3072
	s_add_u32 s26, s26, 0x80000
	s_addc_u32 s27, s27, 0
	s_mov_b32 m0, s50
	ds_read_b128 v[190:193], v148 offset:32768
	ds_read_b128 v[194:197], v148 offset:33792
	ds_read_b128 v[198:201], v148 offset:34816
	ds_read_b128 v[202:205], v148 offset:35840
	ds_read_b128 v[206:209], v148 offset:36864
	ds_read_b128 v[220:223], v148 offset:37888
	ds_read_b128 v[224:227], v148 offset:38912
	ds_read_b128 v[228:231], v148 offset:39936
	global_load_lds_dwordx4 v138, s[26:27]
	s_mov_b32 m0, s51
	s_nop 0
	global_load_lds_dwordx4 v134, s[26:27]
	s_waitcnt vmcnt(8)
	s_waitcnt lgkmcnt(0)
	s_barrier
	s_setprio 1
	s_waitcnt lgkmcnt(0)
	v_mfma_f32_16x16x32_bf16 v[128:131], v[150:153], v[190:193], v[128:131]
	v_mfma_f32_16x16x32_bf16 v[124:127], v[158:161], v[190:193], v[124:127]
	v_mfma_f32_16x16x32_bf16 v[112:115], v[150:153], v[198:201], v[112:115]
	v_mfma_f32_16x16x32_bf16 v[108:111], v[158:161], v[198:201], v[108:111]
	v_mfma_f32_16x16x32_bf16 v[96:99], v[150:153], v[206:209], v[96:99]
	v_mfma_f32_16x16x32_bf16 v[92:95], v[158:161], v[206:209], v[92:95]
	v_mfma_f32_16x16x32_bf16 v[80:83], v[150:153], v[224:227], v[80:83]
	v_mfma_f32_16x16x32_bf16 v[76:79], v[158:161], v[224:227], v[76:79]
	v_mfma_f32_16x16x32_bf16 v[128:131], v[154:157], v[194:197], v[128:131]
	v_mfma_f32_16x16x32_bf16 v[124:127], v[170:173], v[194:197], v[124:127]
	v_mfma_f32_16x16x32_bf16 v[112:115], v[154:157], v[202:205], v[112:115]
	v_mfma_f32_16x16x32_bf16 v[108:111], v[170:173], v[202:205], v[108:111]
	v_mfma_f32_16x16x32_bf16 v[96:99], v[154:157], v[220:223], v[96:99]
	v_mfma_f32_16x16x32_bf16 v[92:95], v[170:173], v[220:223], v[92:95]
	v_mfma_f32_16x16x32_bf16 v[80:83], v[154:157], v[228:231], v[80:83]
	v_mfma_f32_16x16x32_bf16 v[76:79], v[170:173], v[228:231], v[76:79]
	s_setprio 0
	s_setprio 1
	v_mfma_f32_16x16x32_bf16 v[120:123], v[174:177], v[190:193], v[120:123]
	v_mfma_f32_16x16x32_bf16 v[116:119], v[182:185], v[190:193], v[116:119]
	v_mfma_f32_16x16x32_bf16 v[104:107], v[174:177], v[198:201], v[104:107]
	v_mfma_f32_16x16x32_bf16 v[100:103], v[182:185], v[198:201], v[100:103]
	v_mfma_f32_16x16x32_bf16 v[88:91], v[174:177], v[206:209], v[88:91]
	v_mfma_f32_16x16x32_bf16 v[84:87], v[182:185], v[206:209], v[84:87]
	v_mfma_f32_16x16x32_bf16 v[72:75], v[174:177], v[224:227], v[72:75]
	v_mfma_f32_16x16x32_bf16 v[68:71], v[182:185], v[224:227], v[68:71]
	v_mfma_f32_16x16x32_bf16 v[120:123], v[178:181], v[194:197], v[120:123]
	v_mfma_f32_16x16x32_bf16 v[116:119], v[186:189], v[194:197], v[116:119]
	v_mfma_f32_16x16x32_bf16 v[104:107], v[178:181], v[202:205], v[104:107]
	v_mfma_f32_16x16x32_bf16 v[100:103], v[186:189], v[202:205], v[100:103]
	v_mfma_f32_16x16x32_bf16 v[88:91], v[178:181], v[220:223], v[88:91]
	v_mfma_f32_16x16x32_bf16 v[84:87], v[186:189], v[220:223], v[84:87]
	v_mfma_f32_16x16x32_bf16 v[72:75], v[178:181], v[228:231], v[72:75]
	v_mfma_f32_16x16x32_bf16 v[68:71], v[186:189], v[228:231], v[68:71]
	s_setprio 0
	s_barrier
	s_add_i32 m0, s47, 0x17f80
	ds_read_b128 v[190:193], v148 offset:49152
	ds_read_b128 v[194:197], v148 offset:50176
	ds_read_b128 v[198:201], v148 offset:51200
	ds_read_b128 v[202:205], v148 offset:52224
	ds_read_b128 v[206:209], v148 offset:53248
	ds_read_b128 v[220:223], v148 offset:54272
	ds_read_b128 v[224:227], v148 offset:55296
	ds_read_b128 v[228:231], v148 offset:56320
	s_add_u32 s64, s24, 0x7f80
	s_addc_u32 s65, s25, 0
	s_nop 0
	global_load_lds_dwordx4 v136, s[64:65] offset:128
	s_add_i32 m0, s47, 0x19f80
	s_sub_u32 s26, s26, 0x80000
	s_subb_u32 s27, s27, 0
	global_load_lds_dwordx4 v132, s[64:65] offset:128
	s_add_i32 m0, s47, 0x1bf80
	s_nop 0
	s_add_u32 s64, s24, 0xbf80
	s_addc_u32 s65, s25, 0
	s_nop 0
	global_load_lds_dwordx4 v136, s[64:65] offset:128
	s_add_i32 m0, s47, 0x1df80
	s_nop 0
	global_load_lds_dwordx4 v132, s[64:65] offset:128
	s_add_i32 m0, s54, 0xffffff80
	s_nop 0
	global_load_lds_dwordx4 v138, s[26:27] offset:128
	s_add_i32 m0, s55, 0xffffff80
	s_nop 0
	global_load_lds_dwordx4 v134, s[26:27] offset:128
	s_waitcnt vmcnt(8)
	s_waitcnt lgkmcnt(0)
	s_barrier
	s_setprio 1
	s_waitcnt lgkmcnt(0)
	v_mfma_f32_16x16x32_bf16 v[64:67], v[150:153], v[190:193], v[64:67]
	v_mfma_f32_16x16x32_bf16 v[60:63], v[158:161], v[190:193], v[60:63]
	v_mfma_f32_16x16x32_bf16 v[48:51], v[150:153], v[198:201], v[48:51]
	v_mfma_f32_16x16x32_bf16 v[44:47], v[158:161], v[198:201], v[44:47]
	v_mfma_f32_16x16x32_bf16 v[32:35], v[150:153], v[206:209], v[32:35]
	v_mfma_f32_16x16x32_bf16 v[28:31], v[158:161], v[206:209], v[28:31]
	v_mfma_f32_16x16x32_bf16 v[14:17], v[150:153], v[224:227], v[14:17]
	v_mfma_f32_16x16x32_bf16 v[10:13], v[158:161], v[224:227], v[10:13]
	v_mfma_f32_16x16x32_bf16 v[64:67], v[154:157], v[194:197], v[64:67]
	v_mfma_f32_16x16x32_bf16 v[60:63], v[170:173], v[194:197], v[60:63]
	v_mfma_f32_16x16x32_bf16 v[48:51], v[154:157], v[202:205], v[48:51]
	v_mfma_f32_16x16x32_bf16 v[44:47], v[170:173], v[202:205], v[44:47]
	v_mfma_f32_16x16x32_bf16 v[32:35], v[154:157], v[220:223], v[32:35]
	v_mfma_f32_16x16x32_bf16 v[28:31], v[170:173], v[220:223], v[28:31]
	v_mfma_f32_16x16x32_bf16 v[14:17], v[154:157], v[228:231], v[14:17]
	v_mfma_f32_16x16x32_bf16 v[10:13], v[170:173], v[228:231], v[10:13]
	s_setprio 0
	s_setprio 1
	v_mfma_f32_16x16x32_bf16 v[56:59], v[174:177], v[190:193], v[56:59]
	v_mfma_f32_16x16x32_bf16 v[52:55], v[182:185], v[190:193], v[52:55]
	v_mfma_f32_16x16x32_bf16 v[40:43], v[174:177], v[198:201], v[40:43]
	v_mfma_f32_16x16x32_bf16 v[36:39], v[182:185], v[198:201], v[36:39]
	v_mfma_f32_16x16x32_bf16 v[24:27], v[174:177], v[206:209], v[24:27]
	v_mfma_f32_16x16x32_bf16 v[20:23], v[182:185], v[206:209], v[20:23]
	v_mfma_f32_16x16x32_bf16 v[6:9], v[174:177], v[224:227], v[6:9]
	v_mfma_f32_16x16x32_bf16 v[2:5], v[182:185], v[224:227], v[2:5]
	v_mfma_f32_16x16x32_bf16 v[56:59], v[178:181], v[194:197], v[56:59]
	v_mfma_f32_16x16x32_bf16 v[52:55], v[186:189], v[194:197], v[52:55]
	v_mfma_f32_16x16x32_bf16 v[40:43], v[178:181], v[202:205], v[40:43]
	v_mfma_f32_16x16x32_bf16 v[36:39], v[186:189], v[202:205], v[36:39]
	v_mfma_f32_16x16x32_bf16 v[24:27], v[178:181], v[220:223], v[24:27]
	v_mfma_f32_16x16x32_bf16 v[20:23], v[186:189], v[220:223], v[20:23]
	v_mfma_f32_16x16x32_bf16 v[6:9], v[178:181], v[228:231], v[6:9]
	v_mfma_f32_16x16x32_bf16 v[2:5], v[186:189], v[228:231], v[2:5]
	s_setprio 0
	s_barrier
	s_add_i32 s63, s63, 2
	s_add_u32 s61, s61, 0x100
	s_addc_u32 s62, s62, 0
	s_add_u32 s22, s22, 0x100
	s_addc_u32 s23, s23, 0
	s_cmp_gt_u32 s63, 29
	s_cbranch_scc0 .LBB0_1761
	s_and_b64 vcc, exec, s[12:13]
	s_cbranch_vccz .LBB0_1764
	s_barrier
